# GEMM K-loop heads (up-proj, residual, in-proj) aligned to 64 bytes
# baseline (speedup 1.0000x reference)
; #define PG8_STAGE(bufoff, gbase, voff) do { _Pragma("unroll") for (int _i = 0; _i < 2; ++_i) \
;         __builtin_amdgcn_global_load_lds((const unsigned*)((const char*)(gbase) + (voff)[_i]), (PG8_LAS unsigned*)(lds + (bufoff) + ldsw + _i * 8192), 16, 0, 0); } while (0)
; #define PG8_LDA(dst, b, h) do { _Pragma("unroll") for (int m = 0; m < 4; ++m) _Pragma("unroll") for (int k = 0; k < 2; ++k) dst[m][k] = *(const PG8_LAS bf16x8*)(lds + PG8_SA(b, h) + aoff + m * 2048 + k * 1024); } while (0)
; #define PG8_LDB(dst, b, h) do { _Pragma("unroll") for (int n = 0; n < 2; ++n) _Pragma("unroll") for (int k = 0; k < 2; ++k) dst[n][k] = *(const PG8_LAS bf16x8*)(lds + PG8_SB(b, h) + boff + n * 2048 + k * 1024); } while (0)
; #define PG8_WAIT_V(n) asm volatile("s_waitcnt vmcnt(" #n ")" ::: "memory")
; #define PG8_WAIT_L(n) asm volatile("s_waitcnt lgkmcnt(" #n ")" ::: "memory")
; #define PG8_BAR __builtin_amdgcn_s_barrier()
; #define PG8_SCHED __builtin_amdgcn_sched_barrier(0)
; template <class Epi, class Sched, bool ALIGN_EPI = false, bool SP2 = false>
; __device__ __forceinline__ void gemm_phase(PG8_LAS unsigned char* lds, const Gemm g, const Sched& S, const Epi& E) {
;     ...
;         const bool has_next = S.next(ui + 1, nxt);
;         const char* nA = has_next ? (const char*)g.A + (size_t)nxt.pm * tstep : cA; const char* nB = has_next ? (const char*)g.Bt + (size_t)nxt.pn * tstep : cB;
;         for (int t = 0; t < nt; t += 2) {
;             const bool last = (t == nt - 2);
;             const char* a1 = cA + (size_t)(t + 1) * kstep;
;             const char* a2 = last ? nA : cA + (size_t)(t + 2) * kstep; const char* b2 = last ? nB : cB + (size_t)(t + 2) * kstep;
;             const char* a3 = a2 + kstep; const char* b3 = b2 + kstep;
;             if (last && has_next) S.a_ready(nxt);
;             if constexpr (SP2) {
;             PG8_LDB(B0, 0, 0); PG8_LDB(B1, 0, 1); PG8_SCHED; PG8_LDA(At, 0, 0); PG8_STAGE(PG8_SA(1, 1), a1 + hstep, voffA);
;             PG8_WAIT_V(8); PG8_WAIT_L(0); PG8_BAR; PG8_MMA(0, 0, At, B0); PG8_MMA(0, 1, At, B1); PG8_BAR; PG8_SCHED;
;             PG8_LDA(At, 0, 1); PG8_STAGE(PG8_SB(0, 0), b2, voffB); PG8_STAGE(PG8_SB(0, 1), b2 + hstep, voffB); PG8_STAGE(PG8_SA(0, 0), a2, voffA);
;             PG8_WAIT_V(8); PG8_WAIT_L(0); PG8_BAR; PG8_MMA(1, 0, At, B0); PG8_MMA(1, 1, At, B1); PG8_BAR; PG8_SCHED;
.Lstg_done:
	s_ashr_i32 s27, s26, 31
	s_lshl_b64 s[12:13], s[26:27], 20
	s_add_u32 s94, s18, s12
	s_addc_u32 s95, s19, s13
	s_and_b64 s[12:13], s[46:47], exec
	s_cselect_b32 s27, s95, s69
	s_cselect_b32 s86, s94, s68
	s_ashr_i32 s17, s16, 31
	s_lshl_b64 s[12:13], s[16:17], 20
	v_readlane_b32 s14, v254, 38
	v_readlane_b32 s15, v254, 39
	s_add_u32 s14, s14, s12
	s_addc_u32 s15, s15, s13
	s_and_b64 s[12:13], s[46:47], exec
	s_cselect_b32 s17, s15, s11
	s_cselect_b32 s88, s14, s10
	s_add_u32 vcc_lo, s68, 0x80080
	s_addc_u32 vcc_hi, s69, 0
	s_add_u32 s21, s10, 0x100
	s_addc_u32 s12, s11, 0
	s_mov_b32 s13, -2
	v_add_u32_e32 v218, 0x10000, v194
	s_add_u32 s10, vcc_lo, 0xfff80080
	s_addc_u32 s11, vcc_hi, -1
	s_add_i32 s84, 0, 0x10000
	s_cmp_eq_u32 s13, 28
	s_cselect_b32 s69, s27, s11
	s_cselect_b32 s68, s86, s10
	s_cselect_b32 s11, s17, s12
	s_cselect_b32 s10, s88, s21
	s_add_i32 s93, 0, 0x14000
	ds_read_b128 v[114:117], v218
	ds_read_b128 v[118:121], v218 offset:1024
	ds_read_b128 v[130:133], v218 offset:2048
	ds_read_b128 v[138:141], v218 offset:3072
	ds_read_b128 v[146:149], v218 offset:16384
	ds_read_b128 v[156:159], v218 offset:17408
	ds_read_b128 v[160:163], v218 offset:18432
	ds_read_b128 v[164:167], v218 offset:19456
	s_add_i32 m0, s2, 0xc000
	ds_read_b128 v[168:171], v199
	ds_read_b128 v[172:175], v199 offset:1024
	ds_read_b128 v[176:179], v199 offset:2048
	ds_read_b128 v[180:183], v199 offset:3072
	ds_read_b128 v[184:187], v199 offset:4096
	ds_read_b128 v[188:191], v199 offset:5120
	ds_read_b128 v[200:203], v199 offset:6144
	ds_read_b128 v[204:207], v199 offset:7168
	global_load_lds_dwordx4 v152, vcc
	s_add_i32 m0, s2, 0xe000
	s_nop 0
	global_load_lds_dwordx4 v154, vcc
	s_waitcnt vmcnt(8) lgkmcnt(0)
	s_setprio 1
	s_barrier
	v_mfma_f32_16x16x32_bf16 v[142:145], v[114:117], v[168:171], 0
	v_mfma_f32_16x16x32_bf16 v[62:65], v[130:133], v[168:171], 0
	v_mfma_f32_16x16x32_bf16 v[122:125], v[114:117], v[176:179], 0
	v_mfma_f32_16x16x32_bf16 v[50:53], v[130:133], v[176:179], 0
	v_mfma_f32_16x16x32_bf16 v[106:109], v[114:117], v[184:187], 0
	v_mfma_f32_16x16x32_bf16 v[42:45], v[130:133], v[184:187], 0
	v_mfma_f32_16x16x32_bf16 v[98:101], v[114:117], v[200:203], 0
	v_mfma_f32_16x16x32_bf16 v[34:37], v[130:133], v[200:203], 0
	v_mfma_f32_16x16x32_bf16 v[142:145], v[118:121], v[172:175], v[142:145]
	v_mfma_f32_16x16x32_bf16 v[62:65], v[138:141], v[172:175], v[62:65]
	v_mfma_f32_16x16x32_bf16 v[122:125], v[118:121], v[180:183], v[122:125]
	v_mfma_f32_16x16x32_bf16 v[50:53], v[138:141], v[180:183], v[50:53]
	v_mfma_f32_16x16x32_bf16 v[106:109], v[118:121], v[188:191], v[106:109]
	v_mfma_f32_16x16x32_bf16 v[42:45], v[138:141], v[188:191], v[42:45]
	v_mfma_f32_16x16x32_bf16 v[98:101], v[118:121], v[204:207], v[98:101]
	v_mfma_f32_16x16x32_bf16 v[34:37], v[138:141], v[204:207], v[34:37]
	v_mfma_f32_16x16x32_bf16 v[134:137], v[146:149], v[168:171], 0
	v_mfma_f32_16x16x32_bf16 v[58:61], v[160:163], v[168:171], 0
	v_mfma_f32_16x16x32_bf16 v[126:129], v[146:149], v[176:179], 0
	v_mfma_f32_16x16x32_bf16 v[54:57], v[160:163], v[176:179], 0
	v_mfma_f32_16x16x32_bf16 v[110:113], v[146:149], v[184:187], 0
	v_mfma_f32_16x16x32_bf16 v[46:49], v[160:163], v[184:187], 0
	v_mfma_f32_16x16x32_bf16 v[102:105], v[146:149], v[200:203], 0
	v_mfma_f32_16x16x32_bf16 v[38:41], v[160:163], v[200:203], 0
	v_mfma_f32_16x16x32_bf16 v[134:137], v[156:159], v[172:175], v[134:137]
	v_mfma_f32_16x16x32_bf16 v[58:61], v[164:167], v[172:175], v[58:61]
	v_mfma_f32_16x16x32_bf16 v[126:129], v[156:159], v[180:183], v[126:129]
	v_mfma_f32_16x16x32_bf16 v[54:57], v[164:167], v[180:183], v[54:57]
	v_mfma_f32_16x16x32_bf16 v[110:113], v[156:159], v[188:191], v[110:113]
	v_mfma_f32_16x16x32_bf16 v[46:49], v[164:167], v[188:191], v[46:49]
	v_mfma_f32_16x16x32_bf16 v[102:105], v[156:159], v[204:207], v[102:105]
	v_mfma_f32_16x16x32_bf16 v[38:41], v[164:167], v[204:207], v[38:41]
	s_barrier
	s_setprio 0
	s_add_i32 s84, s84, s1
	s_add_u32 s100, s10, 0x80
	s_addc_u32 s101, s11, 0
	s_mov_b32 m0, s84
	ds_read_b128 v[168:171], v199 offset:16384
	ds_read_b128 v[172:175], v199 offset:17408
	ds_read_b128 v[176:179], v199 offset:18432
	ds_read_b128 v[180:183], v199 offset:19456
	ds_read_b128 v[184:187], v199 offset:20480
	ds_read_b128 v[188:191], v199 offset:21504
	ds_read_b128 v[200:203], v199 offset:22528
	ds_read_b128 v[204:207], v199 offset:23552
	global_load_lds_dwordx4 v0, s[10:11]
	s_add_i32 m0, s84, 0x2000
	s_add_u32 s84, s10, 0x80000
	s_addc_u32 s85, s11, 0
	s_add_i32 s93, s93, s1
	global_load_lds_dwordx4 v150, s[10:11]
	s_mov_b32 m0, s93
	s_add_u32 s98, s68, 0x80
	s_addc_u32 s99, s69, 0
	global_load_lds_dwordx4 v0, s[84:85]
	s_add_i32 m0, s93, 0x2000
	s_nop 0
	global_load_lds_dwordx4 v150, s[84:85]
	s_mov_b32 m0, s2
	s_nop 0
	global_load_lds_dwordx4 v0, s[68:69]
	s_mov_b32 m0, s4
	s_nop 0
	global_load_lds_dwordx4 v150, s[68:69]
	s_waitcnt vmcnt(8) lgkmcnt(0)
	s_setprio 1
	s_barrier
; #define PG8_STAGE(bufoff, gbase, voff) do { _Pragma("unroll") for (int _i = 0; _i < 2; ++_i) \
;         __builtin_amdgcn_global_load_lds((const unsigned*)((const char*)(gbase) + (voff)[_i]), (PG8_LAS unsigned*)(lds + (bufoff) + ldsw + _i * 8192), 16, 0, 0); } while (0)
; #define PG8_LDA(dst, b, h) do { _Pragma("unroll") for (int m = 0; m < 4; ++m) _Pragma("unroll") for (int k = 0; k < 2; ++k) dst[m][k] = *(const PG8_LAS bf16x8*)(lds + PG8_SA(b, h) + aoff + m * 2048 + k * 1024); } while (0)
; #define PG8_LDB(dst, b, h) do { _Pragma("unroll") for (int n = 0; n < 2; ++n) _Pragma("unroll") for (int k = 0; k < 2; ++k) dst[n][k] = *(const PG8_LAS bf16x8*)(lds + PG8_SB(b, h) + boff + n * 2048 + k * 1024); } while (0)
; #define PG8_MMA(ai, bj, At, Bt) do { __builtin_amdgcn_s_setprio(1); _Pragma("unroll") for (int m = 0; m < 4; ++m) _Pragma("unroll") for (int n = 0; n < 2; ++n) _Pragma("unroll") for (int k = 0; k < 2; ++k) \
;         acc[ai][bj][m][n] = __builtin_amdgcn_mfma_f32_16x16x32_bf16(Bt[n][k], At[m][k], acc[ai][bj][m][n], 0, 0, 0); __builtin_amdgcn_s_setprio(0); } while (0)
; #define PG8_WAIT_V(n) asm volatile("s_waitcnt vmcnt(" #n ")" ::: "memory")
; #define PG8_WAIT_L(n) asm volatile("s_waitcnt lgkmcnt(" #n ")" ::: "memory")
; #define PG8_BAR __builtin_amdgcn_s_barrier()
; #define PG8_SCHED __builtin_amdgcn_sched_barrier(0)
; template <class Epi, class Sched, bool ALIGN_EPI = false, bool SP2 = false>
; __device__ __forceinline__ void gemm_phase(PG8_LAS unsigned char* lds, const Gemm g, const Sched& S, const Epi& E) {
;     ...
;             PG8_WAIT_V(8); PG8_WAIT_L(0); PG8_BAR; PG8_MMA(0, 0, At, B0); PG8_MMA(0, 1, At, B1); PG8_BAR; PG8_SCHED;
;             PG8_LDA(At, 0, 1); PG8_STAGE(PG8_SB(0, 0), b2, voffB); PG8_STAGE(PG8_SB(0, 1), b2 + hstep, voffB); PG8_STAGE(PG8_SA(0, 0), a2, voffA);
;             PG8_WAIT_V(8); PG8_WAIT_L(0); PG8_BAR; PG8_MMA(1, 0, At, B0); PG8_MMA(1, 1, At, B1); PG8_BAR; PG8_SCHED;
;             PG8_LDB(B0, 1, 0); PG8_LDB(B1, 1, 1); PG8_SCHED; PG8_LDA(At, 1, 0); PG8_STAGE(PG8_SA(0, 1), a2 + hstep, voffA);
;             PG8_WAIT_V(8); PG8_WAIT_L(0); PG8_BAR; PG8_MMA(0, 0, At, B0); PG8_MMA(0, 1, At, B1); PG8_BAR; PG8_SCHED;
	v_mfma_f32_16x16x32_bf16 v[94:97], v[114:117], v[168:171], 0
	v_mfma_f32_16x16x32_bf16 v[30:33], v[130:133], v[168:171], 0
	v_mfma_f32_16x16x32_bf16 v[82:85], v[114:117], v[176:179], 0
	v_mfma_f32_16x16x32_bf16 v[18:21], v[130:133], v[176:179], 0
	v_mfma_f32_16x16x32_bf16 v[74:77], v[114:117], v[184:187], 0
	v_mfma_f32_16x16x32_bf16 v[10:13], v[130:133], v[184:187], 0
	v_mfma_f32_16x16x32_bf16 v[66:69], v[114:117], v[200:203], 0
	v_mfma_f32_16x16x32_bf16 v[2:5], v[130:133], v[200:203], 0
	v_mfma_f32_16x16x32_bf16 v[94:97], v[118:121], v[172:175], v[94:97]
	v_mfma_f32_16x16x32_bf16 v[30:33], v[138:141], v[172:175], v[30:33]
	v_mfma_f32_16x16x32_bf16 v[82:85], v[118:121], v[180:183], v[82:85]
	v_mfma_f32_16x16x32_bf16 v[18:21], v[138:141], v[180:183], v[18:21]
	v_mfma_f32_16x16x32_bf16 v[74:77], v[118:121], v[188:191], v[74:77]
	v_mfma_f32_16x16x32_bf16 v[10:13], v[138:141], v[188:191], v[10:13]
	v_mfma_f32_16x16x32_bf16 v[66:69], v[118:121], v[204:207], v[66:69]
	v_mfma_f32_16x16x32_bf16 v[2:5], v[138:141], v[204:207], v[2:5]
	v_mfma_f32_16x16x32_bf16 v[90:93], v[146:149], v[168:171], 0
	v_mfma_f32_16x16x32_bf16 v[26:29], v[160:163], v[168:171], 0
	v_mfma_f32_16x16x32_bf16 v[86:89], v[146:149], v[176:179], 0
	v_mfma_f32_16x16x32_bf16 v[22:25], v[160:163], v[176:179], 0
	v_mfma_f32_16x16x32_bf16 v[78:81], v[146:149], v[184:187], 0
	v_mfma_f32_16x16x32_bf16 v[14:17], v[160:163], v[184:187], 0
	v_mfma_f32_16x16x32_bf16 v[70:73], v[146:149], v[200:203], 0
	v_mfma_f32_16x16x32_bf16 v[6:9], v[160:163], v[200:203], 0
	v_mfma_f32_16x16x32_bf16 v[90:93], v[156:159], v[172:175], v[90:93]
	v_mfma_f32_16x16x32_bf16 v[26:29], v[164:167], v[172:175], v[26:29]
	v_mfma_f32_16x16x32_bf16 v[86:89], v[156:159], v[180:183], v[86:89]
	v_mfma_f32_16x16x32_bf16 v[22:25], v[164:167], v[180:183], v[22:25]
	v_mfma_f32_16x16x32_bf16 v[78:81], v[156:159], v[188:191], v[78:81]
	v_mfma_f32_16x16x32_bf16 v[14:17], v[164:167], v[188:191], v[14:17]
	v_mfma_f32_16x16x32_bf16 v[70:73], v[156:159], v[204:207], v[70:73]
	v_mfma_f32_16x16x32_bf16 v[6:9], v[164:167], v[204:207], v[6:9]
	s_barrier
	s_setprio 0
	s_add_i32 s84, 0, 0x18000
	s_add_i32 s85, 0, 0x1c000
	ds_read_b128 v[114:117], v218 offset:32768
	ds_read_b128 v[118:121], v218 offset:33792
	ds_read_b128 v[130:133], v218 offset:34816
	ds_read_b128 v[138:141], v218 offset:35840
	ds_read_b128 v[146:149], v218 offset:49152
	ds_read_b128 v[156:159], v218 offset:50176
	ds_read_b128 v[160:163], v218 offset:51200
	ds_read_b128 v[164:167], v218 offset:52224
	s_add_u32 s68, s68, 0x80000
	s_addc_u32 s69, s69, 0
	s_mov_b32 m0, s5
	ds_read_b128 v[168:171], v199 offset:32768
	ds_read_b128 v[172:175], v199 offset:33792
	ds_read_b128 v[176:179], v199 offset:34816
	ds_read_b128 v[180:183], v199 offset:35840
	ds_read_b128 v[184:187], v199 offset:36864
	ds_read_b128 v[188:191], v199 offset:37888
	ds_read_b128 v[200:203], v199 offset:38912
	ds_read_b128 v[204:207], v199 offset:39936
	global_load_lds_dwordx4 v0, s[68:69]
	s_mov_b32 m0, s6
	s_nop 0
	global_load_lds_dwordx4 v150, s[68:69]
	s_waitcnt vmcnt(8) lgkmcnt(0)
	s_setprio 1
	s_barrier
	v_mfma_f32_16x16x32_bf16 v[142:145], v[114:117], v[168:171], v[142:145]
	v_mfma_f32_16x16x32_bf16 v[62:65], v[130:133], v[168:171], v[62:65]
	v_mfma_f32_16x16x32_bf16 v[122:125], v[114:117], v[176:179], v[122:125]
	v_mfma_f32_16x16x32_bf16 v[50:53], v[130:133], v[176:179], v[50:53]
	v_mfma_f32_16x16x32_bf16 v[106:109], v[114:117], v[184:187], v[106:109]
	v_mfma_f32_16x16x32_bf16 v[42:45], v[130:133], v[184:187], v[42:45]
	v_mfma_f32_16x16x32_bf16 v[98:101], v[114:117], v[200:203], v[98:101]
	v_mfma_f32_16x16x32_bf16 v[34:37], v[130:133], v[200:203], v[34:37]
	v_mfma_f32_16x16x32_bf16 v[142:145], v[118:121], v[172:175], v[142:145]
	v_mfma_f32_16x16x32_bf16 v[62:65], v[138:141], v[172:175], v[62:65]
	v_mfma_f32_16x16x32_bf16 v[122:125], v[118:121], v[180:183], v[122:125]
	v_mfma_f32_16x16x32_bf16 v[50:53], v[138:141], v[180:183], v[50:53]
	v_mfma_f32_16x16x32_bf16 v[106:109], v[118:121], v[188:191], v[106:109]
	v_mfma_f32_16x16x32_bf16 v[42:45], v[138:141], v[188:191], v[42:45]
	v_mfma_f32_16x16x32_bf16 v[98:101], v[118:121], v[204:207], v[98:101]
	v_mfma_f32_16x16x32_bf16 v[34:37], v[138:141], v[204:207], v[34:37]
	v_mfma_f32_16x16x32_bf16 v[134:137], v[146:149], v[168:171], v[134:137]
	v_mfma_f32_16x16x32_bf16 v[58:61], v[160:163], v[168:171], v[58:61]
	v_mfma_f32_16x16x32_bf16 v[126:129], v[146:149], v[176:179], v[126:129]
	v_mfma_f32_16x16x32_bf16 v[54:57], v[160:163], v[176:179], v[54:57]
	v_mfma_f32_16x16x32_bf16 v[110:113], v[146:149], v[184:187], v[110:113]
	v_mfma_f32_16x16x32_bf16 v[46:49], v[160:163], v[184:187], v[46:49]
	v_mfma_f32_16x16x32_bf16 v[102:105], v[146:149], v[200:203], v[102:105]
	v_mfma_f32_16x16x32_bf16 v[38:41], v[160:163], v[200:203], v[38:41]
	v_mfma_f32_16x16x32_bf16 v[134:137], v[156:159], v[172:175], v[134:137]
	v_mfma_f32_16x16x32_bf16 v[58:61], v[164:167], v[172:175], v[58:61]
	v_mfma_f32_16x16x32_bf16 v[126:129], v[156:159], v[180:183], v[126:129]
	v_mfma_f32_16x16x32_bf16 v[54:57], v[164:167], v[180:183], v[54:57]
	v_mfma_f32_16x16x32_bf16 v[110:113], v[156:159], v[188:191], v[110:113]
	v_mfma_f32_16x16x32_bf16 v[46:49], v[164:167], v[188:191], v[46:49]
	v_mfma_f32_16x16x32_bf16 v[102:105], v[156:159], v[204:207], v[102:105]
	v_mfma_f32_16x16x32_bf16 v[38:41], v[164:167], v[204:207], v[38:41]
	s_barrier
; #define PG8_STAGE(bufoff, gbase, voff) do { _Pragma("unroll") for (int _i = 0; _i < 2; ++_i) \
;         __builtin_amdgcn_global_load_lds((const unsigned*)((const char*)(gbase) + (voff)[_i]), (PG8_LAS unsigned*)(lds + (bufoff) + ldsw + _i * 8192), 16, 0, 0); } while (0)
; #define PG8_LDA(dst, b, h) do { _Pragma("unroll") for (int m = 0; m < 4; ++m) _Pragma("unroll") for (int k = 0; k < 2; ++k) dst[m][k] = *(const PG8_LAS bf16x8*)(lds + PG8_SA(b, h) + aoff + m * 2048 + k * 1024); } while (0)
; #define PG8_MMA(ai, bj, At, Bt) do { __builtin_amdgcn_s_setprio(1); _Pragma("unroll") for (int m = 0; m < 4; ++m) _Pragma("unroll") for (int n = 0; n < 2; ++n) _Pragma("unroll") for (int k = 0; k < 2; ++k) \
;         acc[ai][bj][m][n] = __builtin_amdgcn_mfma_f32_16x16x32_bf16(Bt[n][k], At[m][k], acc[ai][bj][m][n], 0, 0, 0); __builtin_amdgcn_s_setprio(0); } while (0)
; #define PG8_WAIT_V(n) asm volatile("s_waitcnt vmcnt(" #n ")" ::: "memory")
; #define PG8_WAIT_L(n) asm volatile("s_waitcnt lgkmcnt(" #n ")" ::: "memory")
; #define PG8_BAR __builtin_amdgcn_s_barrier()
; #define PG8_SCHED __builtin_amdgcn_sched_barrier(0)
; template <class Epi, class Sched, bool ALIGN_EPI = false, bool SP2 = false>
; __device__ __forceinline__ void gemm_phase(PG8_LAS unsigned char* lds, const Gemm g, const Sched& S, const Epi& E) {
;     ...
;             PG8_LDA(At, 1, 1); PG8_STAGE(PG8_SB(1, 0), b3, voffB); PG8_STAGE(PG8_SB(1, 1), b3 + hstep, voffB); PG8_STAGE(PG8_SA(1, 0), a3, voffA);
;             PG8_WAIT_V(8); PG8_WAIT_L(0); PG8_BAR; PG8_MMA(1, 0, At, B0); PG8_MMA(1, 1, At, B1); PG8_BAR; PG8_SCHED;
	s_setprio 0
	s_add_i32 s68, s84, s1
	s_mov_b32 m0, s68
	ds_read_b128 v[168:171], v199 offset:49152
	ds_read_b128 v[172:175], v199 offset:50176
	ds_read_b128 v[176:179], v199 offset:51200
	ds_read_b128 v[180:183], v199 offset:52224
	ds_read_b128 v[184:187], v199 offset:53248
	ds_read_b128 v[188:191], v199 offset:54272
	ds_read_b128 v[200:203], v199 offset:55296
	ds_read_b128 v[204:207], v199 offset:56320
	global_load_lds_dwordx4 v0, s[100:101]
	s_add_i32 m0, s68, 0x2000
	s_add_i32 s68, s85, s1
	global_load_lds_dwordx4 v150, s[100:101]
	s_add_u32 s10, s10, 0x80080
	s_addc_u32 s11, s11, 0
	s_mov_b32 m0, s68
	s_nop 0
	global_load_lds_dwordx4 v0, s[10:11]
	s_add_i32 m0, s68, 0x2000
	s_nop 0
	global_load_lds_dwordx4 v150, s[10:11]
	s_mov_b32 m0, s7
	s_nop 0
	global_load_lds_dwordx4 v0, s[98:99]
	s_mov_b32 m0, s30
	s_nop 0
	global_load_lds_dwordx4 v150, s[98:99]
	s_waitcnt vmcnt(8) lgkmcnt(0)
	s_setprio 1
	s_barrier
	v_mfma_f32_16x16x32_bf16 v[94:97], v[114:117], v[168:171], v[94:97]
	v_mfma_f32_16x16x32_bf16 v[30:33], v[130:133], v[168:171], v[30:33]
	v_mfma_f32_16x16x32_bf16 v[82:85], v[114:117], v[176:179], v[82:85]
	v_mfma_f32_16x16x32_bf16 v[18:21], v[130:133], v[176:179], v[18:21]
	v_mfma_f32_16x16x32_bf16 v[74:77], v[114:117], v[184:187], v[74:77]
	v_mfma_f32_16x16x32_bf16 v[10:13], v[130:133], v[184:187], v[10:13]
	v_mfma_f32_16x16x32_bf16 v[66:69], v[114:117], v[200:203], v[66:69]
	v_mfma_f32_16x16x32_bf16 v[2:5], v[130:133], v[200:203], v[2:5]
	v_mfma_f32_16x16x32_bf16 v[94:97], v[118:121], v[172:175], v[94:97]
	v_mfma_f32_16x16x32_bf16 v[30:33], v[138:141], v[172:175], v[30:33]
	v_mfma_f32_16x16x32_bf16 v[82:85], v[118:121], v[180:183], v[82:85]
	v_mfma_f32_16x16x32_bf16 v[18:21], v[138:141], v[180:183], v[18:21]
	v_mfma_f32_16x16x32_bf16 v[74:77], v[118:121], v[188:191], v[74:77]
	v_mfma_f32_16x16x32_bf16 v[10:13], v[138:141], v[188:191], v[10:13]
	v_mfma_f32_16x16x32_bf16 v[66:69], v[118:121], v[204:207], v[66:69]
	v_mfma_f32_16x16x32_bf16 v[2:5], v[138:141], v[204:207], v[2:5]
	v_mfma_f32_16x16x32_bf16 v[90:93], v[146:149], v[168:171], v[90:93]
	v_mfma_f32_16x16x32_bf16 v[26:29], v[160:163], v[168:171], v[26:29]
	v_mfma_f32_16x16x32_bf16 v[86:89], v[146:149], v[176:179], v[86:89]
	v_mfma_f32_16x16x32_bf16 v[22:25], v[160:163], v[176:179], v[22:25]
	v_mfma_f32_16x16x32_bf16 v[78:81], v[146:149], v[184:187], v[78:81]
	v_mfma_f32_16x16x32_bf16 v[14:17], v[160:163], v[184:187], v[14:17]
	v_mfma_f32_16x16x32_bf16 v[70:73], v[146:149], v[200:203], v[70:73]
	v_mfma_f32_16x16x32_bf16 v[6:9], v[160:163], v[200:203], v[6:9]
	v_mfma_f32_16x16x32_bf16 v[90:93], v[156:159], v[172:175], v[90:93]
	v_mfma_f32_16x16x32_bf16 v[26:29], v[164:167], v[172:175], v[26:29]
	v_mfma_f32_16x16x32_bf16 v[86:89], v[156:159], v[180:183], v[86:89]
	v_mfma_f32_16x16x32_bf16 v[22:25], v[164:167], v[180:183], v[22:25]
	v_mfma_f32_16x16x32_bf16 v[78:81], v[156:159], v[188:191], v[78:81]
	v_mfma_f32_16x16x32_bf16 v[14:17], v[164:167], v[188:191], v[14:17]
	v_mfma_f32_16x16x32_bf16 v[70:73], v[156:159], v[204:207], v[70:73]
	v_mfma_f32_16x16x32_bf16 v[6:9], v[164:167], v[204:207], v[6:9]
	s_barrier
	s_setprio 0
	s_add_i32 s13, s13, 2
	s_add_u32 vcc_lo, vcc_lo, 0x100
	s_addc_u32 vcc_hi, vcc_hi, 0
	s_add_u32 s21, s21, 0x100
	s_addc_u32 s12, s12, 0
	.p2align 6

; #define PG8_STAGE(bufoff, gbase, voff) do { _Pragma("unroll") for (int _i = 0; _i < 2; ++_i) \
;         __builtin_amdgcn_global_load_lds((const unsigned*)((const char*)(gbase) + (voff)[_i]), (PG8_LAS unsigned*)(lds + (bufoff) + ldsw + _i * 8192), 16, 0, 0); } while (0)
; #define PG8_LDA(dst, b, h) do { _Pragma("unroll") for (int m = 0; m < 4; ++m) _Pragma("unroll") for (int k = 0; k < 2; ++k) dst[m][k] = *(const PG8_LAS bf16x8*)(lds + PG8_SA(b, h) + aoff + m * 2048 + k * 1024); } while (0)
; #define PG8_LDB(dst, b, h) do { _Pragma("unroll") for (int n = 0; n < 2; ++n) _Pragma("unroll") for (int k = 0; k < 2; ++k) dst[n][k] = *(const PG8_LAS bf16x8*)(lds + PG8_SB(b, h) + boff + n * 2048 + k * 1024); } while (0)
; #define PG8_WAIT_V(n) asm volatile("s_waitcnt vmcnt(" #n ")" ::: "memory")
; #define PG8_WAIT_L(n) asm volatile("s_waitcnt lgkmcnt(" #n ")" ::: "memory")
; #define PG8_BAR __builtin_amdgcn_s_barrier()
; #define PG8_SCHED __builtin_amdgcn_sched_barrier(0)
; template <class Epi, class Sched, bool ALIGN_EPI = false, bool SP2 = false>
; __device__ __forceinline__ void gemm_phase(PG8_LAS unsigned char* lds, const Gemm g, const Sched& S, const Epi& E) {
;     ...
;         const char* nA = has_next ? (const char*)g.A + (size_t)nxt.pm * tstep : cA; const char* nB = has_next ? (const char*)g.Bt + (size_t)nxt.pn * tstep : cB;
;         for (int t = 0; t < nt; t += 2) {
;             const bool last = (t == nt - 2);
;             const char* a1 = cA + (size_t)(t + 1) * kstep;
;             const char* a2 = last ? nA : cA + (size_t)(t + 2) * kstep; const char* b2 = last ? nB : cB + (size_t)(t + 2) * kstep;
;             const char* a3 = a2 + kstep; const char* b3 = b2 + kstep;
;             if (last && has_next) S.a_ready(nxt);
;             if constexpr (SP2) {
;             PG8_LDB(B0, 0, 0); PG8_LDB(B1, 0, 1); PG8_SCHED; PG8_LDA(At, 0, 0); PG8_STAGE(PG8_SA(1, 1), a1 + hstep, voffA);
;             PG8_WAIT_V(8); PG8_WAIT_L(0); PG8_BAR; PG8_MMA(0, 0, At, B0); PG8_MMA(0, 1, At, B1); PG8_BAR; PG8_SCHED;
;             PG8_LDA(At, 0, 1); PG8_STAGE(PG8_SB(0, 0), b2, voffB); PG8_STAGE(PG8_SB(0, 1), b2 + hstep, voffB); PG8_STAGE(PG8_SA(0, 0), a2, voffA);
;             PG8_WAIT_V(8); PG8_WAIT_L(0); PG8_BAR; PG8_MMA(1, 0, At, B0); PG8_MMA(1, 1, At, B1); PG8_BAR; PG8_SCHED;
.LBB0_222:
	s_add_u32 s8, s8, 0x80
	s_addc_u32 s9, s9, 0
	s_add_u32 s12, s10, 0x100
	s_addc_u32 s13, s11, 0
	s_mov_b32 s10, 0
	s_waitcnt lgkmcnt(0)
	v_add_u32_e32 v218, 0x10000, v145
	s_add_i32 s14, s10, 2
	s_add_u32 s15, s8, 0x80
	s_addc_u32 s11, s9, 0
	s_add_i32 s64, 0, 0x10000
	s_cmp_eq_u32 s57, s10
	s_cselect_b32 s11, s51, s11
	s_cselect_b32 s10, s50, s15
	s_cselect_b32 s45, s53, s13
	s_cselect_b32 s44, s52, s12
	s_add_i32 s15, 0, 0x14000
	ds_read_b128 v[140:143], v218
	ds_read_b128 v[148:151], v218 offset:1024
	ds_read_b128 v[152:155], v218 offset:2048
	ds_read_b128 v[156:159], v218 offset:3072
	ds_read_b128 v[160:163], v218 offset:16384
	ds_read_b128 v[164:167], v218 offset:17408
	ds_read_b128 v[168:171], v218 offset:18432
	ds_read_b128 v[172:175], v218 offset:19456
	s_add_i32 m0, s21, 0xc000
	ds_read_b128 v[176:179], v147
	ds_read_b128 v[180:183], v147 offset:1024
	ds_read_b128 v[184:187], v147 offset:2048
	ds_read_b128 v[188:191], v147 offset:3072
	ds_read_b128 v[192:195], v147 offset:4096
	ds_read_b128 v[196:199], v147 offset:5120
	ds_read_b128 v[200:203], v147 offset:6144
	ds_read_b128 v[204:207], v147 offset:7168
	global_load_lds_dwordx4 v136, s[8:9]
	s_add_i32 m0, s21, 0xe000
	s_nop 0
	global_load_lds_dwordx4 v138, s[8:9]
	s_waitcnt vmcnt(8) lgkmcnt(0)
	s_setprio 1
	s_barrier
	v_mfma_f32_16x16x32_bf16 v[126:129], v[140:143], v[176:179], 0
	v_mfma_f32_16x16x32_bf16 v[122:125], v[152:155], v[176:179], 0
	v_mfma_f32_16x16x32_bf16 v[110:113], v[140:143], v[184:187], 0
	v_mfma_f32_16x16x32_bf16 v[106:109], v[152:155], v[184:187], 0
	v_mfma_f32_16x16x32_bf16 v[94:97], v[140:143], v[192:195], 0
	v_mfma_f32_16x16x32_bf16 v[90:93], v[152:155], v[192:195], 0
	v_mfma_f32_16x16x32_bf16 v[78:81], v[140:143], v[200:203], 0
	v_mfma_f32_16x16x32_bf16 v[74:77], v[152:155], v[200:203], 0
	v_mfma_f32_16x16x32_bf16 v[126:129], v[148:151], v[180:183], v[126:129]
	v_mfma_f32_16x16x32_bf16 v[122:125], v[156:159], v[180:183], v[122:125]
	v_mfma_f32_16x16x32_bf16 v[110:113], v[148:151], v[188:191], v[110:113]
	v_mfma_f32_16x16x32_bf16 v[106:109], v[156:159], v[188:191], v[106:109]
	v_mfma_f32_16x16x32_bf16 v[94:97], v[148:151], v[196:199], v[94:97]
	v_mfma_f32_16x16x32_bf16 v[90:93], v[156:159], v[196:199], v[90:93]
	v_mfma_f32_16x16x32_bf16 v[78:81], v[148:151], v[204:207], v[78:81]
	v_mfma_f32_16x16x32_bf16 v[74:77], v[156:159], v[204:207], v[74:77]
	v_mfma_f32_16x16x32_bf16 v[118:121], v[160:163], v[176:179], 0
	v_mfma_f32_16x16x32_bf16 v[114:117], v[168:171], v[176:179], 0
	v_mfma_f32_16x16x32_bf16 v[102:105], v[160:163], v[184:187], 0
	v_mfma_f32_16x16x32_bf16 v[98:101], v[168:171], v[184:187], 0
	v_mfma_f32_16x16x32_bf16 v[86:89], v[160:163], v[192:195], 0
	v_mfma_f32_16x16x32_bf16 v[82:85], v[168:171], v[192:195], 0
	v_mfma_f32_16x16x32_bf16 v[70:73], v[160:163], v[200:203], 0
	v_mfma_f32_16x16x32_bf16 v[66:69], v[168:171], v[200:203], 0
	v_mfma_f32_16x16x32_bf16 v[118:121], v[164:167], v[180:183], v[118:121]
	v_mfma_f32_16x16x32_bf16 v[114:117], v[172:175], v[180:183], v[114:117]
	v_mfma_f32_16x16x32_bf16 v[102:105], v[164:167], v[188:191], v[102:105]
	v_mfma_f32_16x16x32_bf16 v[98:101], v[172:175], v[188:191], v[98:101]
	v_mfma_f32_16x16x32_bf16 v[86:89], v[164:167], v[196:199], v[86:89]
	v_mfma_f32_16x16x32_bf16 v[82:85], v[172:175], v[196:199], v[82:85]
	v_mfma_f32_16x16x32_bf16 v[70:73], v[164:167], v[204:207], v[70:73]
	v_mfma_f32_16x16x32_bf16 v[66:69], v[172:175], v[204:207], v[66:69]
	s_barrier
	s_setprio 0
	s_add_i32 s64, s64, s7
	s_add_u32 s98, s44, 0x80
	s_addc_u32 s99, s45, 0
	s_mov_b32 m0, s64
	ds_read_b128 v[176:179], v147 offset:16384
	ds_read_b128 v[180:183], v147 offset:17408
	ds_read_b128 v[184:187], v147 offset:18432
	ds_read_b128 v[188:191], v147 offset:19456
	ds_read_b128 v[192:195], v147 offset:20480
	ds_read_b128 v[196:199], v147 offset:21504
	ds_read_b128 v[200:203], v147 offset:22528
	ds_read_b128 v[204:207], v147 offset:23552
	global_load_lds_dwordx4 v0, s[44:45]
	s_add_i32 m0, s64, 0x2000
	s_add_i32 s15, s15, s7
	global_load_lds_dwordx4 v134, s[44:45]
	s_add_u32 s44, s44, s30
	s_addc_u32 s45, s45, 0
	s_add_u32 s100, s44, 0x80
	s_addc_u32 s101, s45, 0
	s_mov_b32 m0, s15
	s_add_u32 vcc_lo, s10, 0x80
	s_addc_u32 vcc_hi, s11, 0
	global_load_lds_dwordx4 v0, s[44:45]
	s_add_i32 m0, s15, 0x2000
	s_nop 0
	global_load_lds_dwordx4 v134, s[44:45]
	s_mov_b32 m0, s21
	s_nop 0
	global_load_lds_dwordx4 v130, s[10:11]
	s_mov_b32 m0, s26
	s_nop 0
	global_load_lds_dwordx4 v132, s[10:11]
	s_waitcnt vmcnt(8) lgkmcnt(0)
	s_setprio 1
	s_barrier
	v_mfma_f32_16x16x32_bf16 v[62:65], v[140:143], v[176:179], 0
	v_mfma_f32_16x16x32_bf16 v[58:61], v[152:155], v[176:179], 0
	v_mfma_f32_16x16x32_bf16 v[46:49], v[140:143], v[184:187], 0
	v_mfma_f32_16x16x32_bf16 v[42:45], v[152:155], v[184:187], 0
	v_mfma_f32_16x16x32_bf16 v[30:33], v[140:143], v[192:195], 0
	v_mfma_f32_16x16x32_bf16 v[26:29], v[152:155], v[192:195], 0
	v_mfma_f32_16x16x32_bf16 v[14:17], v[140:143], v[200:203], 0
	v_mfma_f32_16x16x32_bf16 v[10:13], v[152:155], v[200:203], 0
	v_mfma_f32_16x16x32_bf16 v[62:65], v[148:151], v[180:183], v[62:65]
	v_mfma_f32_16x16x32_bf16 v[58:61], v[156:159], v[180:183], v[58:61]
	v_mfma_f32_16x16x32_bf16 v[46:49], v[148:151], v[188:191], v[46:49]
	v_mfma_f32_16x16x32_bf16 v[42:45], v[156:159], v[188:191], v[42:45]
	v_mfma_f32_16x16x32_bf16 v[30:33], v[148:151], v[196:199], v[30:33]
	v_mfma_f32_16x16x32_bf16 v[26:29], v[156:159], v[196:199], v[26:29]
	v_mfma_f32_16x16x32_bf16 v[14:17], v[148:151], v[204:207], v[14:17]
	v_mfma_f32_16x16x32_bf16 v[10:13], v[156:159], v[204:207], v[10:13]
	v_mfma_f32_16x16x32_bf16 v[54:57], v[160:163], v[176:179], 0
	v_mfma_f32_16x16x32_bf16 v[50:53], v[168:171], v[176:179], 0
	v_mfma_f32_16x16x32_bf16 v[38:41], v[160:163], v[184:187], 0
	v_mfma_f32_16x16x32_bf16 v[34:37], v[168:171], v[184:187], 0
	v_mfma_f32_16x16x32_bf16 v[22:25], v[160:163], v[192:195], 0
	v_mfma_f32_16x16x32_bf16 v[18:21], v[168:171], v[192:195], 0
	v_mfma_f32_16x16x32_bf16 v[6:9], v[160:163], v[200:203], 0
	v_mfma_f32_16x16x32_bf16 v[2:5], v[168:171], v[200:203], 0
	v_mfma_f32_16x16x32_bf16 v[54:57], v[164:167], v[180:183], v[54:57]
	v_mfma_f32_16x16x32_bf16 v[50:53], v[172:175], v[180:183], v[50:53]
	v_mfma_f32_16x16x32_bf16 v[38:41], v[164:167], v[188:191], v[38:41]
	v_mfma_f32_16x16x32_bf16 v[34:37], v[172:175], v[188:191], v[34:37]
	v_mfma_f32_16x16x32_bf16 v[22:25], v[164:167], v[196:199], v[22:25]
	v_mfma_f32_16x16x32_bf16 v[18:21], v[172:175], v[196:199], v[18:21]
	v_mfma_f32_16x16x32_bf16 v[6:9], v[164:167], v[204:207], v[6:9]
	v_mfma_f32_16x16x32_bf16 v[2:5], v[172:175], v[204:207], v[2:5]
	s_barrier
; #define PG8_STAGE(bufoff, gbase, voff) do { _Pragma("unroll") for (int _i = 0; _i < 2; ++_i) \
;         __builtin_amdgcn_global_load_lds((const unsigned*)((const char*)(gbase) + (voff)[_i]), (PG8_LAS unsigned*)(lds + (bufoff) + ldsw + _i * 8192), 16, 0, 0); } while (0)
; #define PG8_LDA(dst, b, h) do { _Pragma("unroll") for (int m = 0; m < 4; ++m) _Pragma("unroll") for (int k = 0; k < 2; ++k) dst[m][k] = *(const PG8_LAS bf16x8*)(lds + PG8_SA(b, h) + aoff + m * 2048 + k * 1024); } while (0)
; #define PG8_LDB(dst, b, h) do { _Pragma("unroll") for (int n = 0; n < 2; ++n) _Pragma("unroll") for (int k = 0; k < 2; ++k) dst[n][k] = *(const PG8_LAS bf16x8*)(lds + PG8_SB(b, h) + boff + n * 2048 + k * 1024); } while (0)
; #define PG8_MMA(ai, bj, At, Bt) do { __builtin_amdgcn_s_setprio(1); _Pragma("unroll") for (int m = 0; m < 4; ++m) _Pragma("unroll") for (int n = 0; n < 2; ++n) _Pragma("unroll") for (int k = 0; k < 2; ++k) \
;         acc[ai][bj][m][n] = __builtin_amdgcn_mfma_f32_16x16x32_bf16(Bt[n][k], At[m][k], acc[ai][bj][m][n], 0, 0, 0); __builtin_amdgcn_s_setprio(0); } while (0)
; #define PG8_WAIT_V(n) asm volatile("s_waitcnt vmcnt(" #n ")" ::: "memory")
; #define PG8_WAIT_L(n) asm volatile("s_waitcnt lgkmcnt(" #n ")" ::: "memory")
; #define PG8_BAR __builtin_amdgcn_s_barrier()
; #define PG8_SCHED __builtin_amdgcn_sched_barrier(0)
; template <class Epi, class Sched, bool ALIGN_EPI = false, bool SP2 = false>
; __device__ __forceinline__ void gemm_phase(PG8_LAS unsigned char* lds, const Gemm g, const Sched& S, const Epi& E) {
;     ...
;             PG8_LDB(B0, 1, 0); PG8_LDB(B1, 1, 1); PG8_SCHED; PG8_LDA(At, 1, 0); PG8_STAGE(PG8_SA(0, 1), a2 + hstep, voffA);
;             PG8_WAIT_V(8); PG8_WAIT_L(0); PG8_BAR; PG8_MMA(0, 0, At, B0); PG8_MMA(0, 1, At, B1); PG8_BAR; PG8_SCHED;
;             PG8_LDA(At, 1, 1); PG8_STAGE(PG8_SB(1, 0), b3, voffB); PG8_STAGE(PG8_SB(1, 1), b3 + hstep, voffB); PG8_STAGE(PG8_SA(1, 0), a3, voffA);
;             PG8_WAIT_V(8); PG8_WAIT_L(0); PG8_BAR; PG8_MMA(1, 0, At, B0); PG8_MMA(1, 1, At, B1); PG8_BAR; PG8_SCHED;
	s_setprio 0
	s_add_i32 s15, 0, 0x18000
	s_add_i32 s44, 0, 0x1c000
	ds_read_b128 v[140:143], v218 offset:32768
	ds_read_b128 v[148:151], v218 offset:33792
	ds_read_b128 v[152:155], v218 offset:34816
	ds_read_b128 v[156:159], v218 offset:35840
	ds_read_b128 v[160:163], v218 offset:49152
	ds_read_b128 v[164:167], v218 offset:50176
	ds_read_b128 v[168:171], v218 offset:51200
	ds_read_b128 v[172:175], v218 offset:52224
	s_add_u32 s10, s10, s30
	s_addc_u32 s11, s11, 0
	s_mov_b32 m0, s27
	ds_read_b128 v[176:179], v147 offset:32768
	ds_read_b128 v[180:183], v147 offset:33792
	ds_read_b128 v[184:187], v147 offset:34816
	ds_read_b128 v[188:191], v147 offset:35840
	ds_read_b128 v[192:195], v147 offset:36864
	ds_read_b128 v[196:199], v147 offset:37888
	ds_read_b128 v[200:203], v147 offset:38912
	ds_read_b128 v[204:207], v147 offset:39936
	global_load_lds_dwordx4 v130, s[10:11]
	s_mov_b32 m0, s54
	s_nop 0
	global_load_lds_dwordx4 v132, s[10:11]
	s_waitcnt vmcnt(8) lgkmcnt(0)
	s_setprio 1
	s_barrier
	v_mfma_f32_16x16x32_bf16 v[126:129], v[140:143], v[176:179], v[126:129]
	v_mfma_f32_16x16x32_bf16 v[122:125], v[152:155], v[176:179], v[122:125]
	v_mfma_f32_16x16x32_bf16 v[110:113], v[140:143], v[184:187], v[110:113]
	v_mfma_f32_16x16x32_bf16 v[106:109], v[152:155], v[184:187], v[106:109]
	v_mfma_f32_16x16x32_bf16 v[94:97], v[140:143], v[192:195], v[94:97]
	v_mfma_f32_16x16x32_bf16 v[90:93], v[152:155], v[192:195], v[90:93]
	v_mfma_f32_16x16x32_bf16 v[78:81], v[140:143], v[200:203], v[78:81]
	v_mfma_f32_16x16x32_bf16 v[74:77], v[152:155], v[200:203], v[74:77]
	v_mfma_f32_16x16x32_bf16 v[126:129], v[148:151], v[180:183], v[126:129]
	v_mfma_f32_16x16x32_bf16 v[122:125], v[156:159], v[180:183], v[122:125]
	v_mfma_f32_16x16x32_bf16 v[110:113], v[148:151], v[188:191], v[110:113]
	v_mfma_f32_16x16x32_bf16 v[106:109], v[156:159], v[188:191], v[106:109]
	v_mfma_f32_16x16x32_bf16 v[94:97], v[148:151], v[196:199], v[94:97]
	v_mfma_f32_16x16x32_bf16 v[90:93], v[156:159], v[196:199], v[90:93]
	v_mfma_f32_16x16x32_bf16 v[78:81], v[148:151], v[204:207], v[78:81]
	v_mfma_f32_16x16x32_bf16 v[74:77], v[156:159], v[204:207], v[74:77]
	v_mfma_f32_16x16x32_bf16 v[118:121], v[160:163], v[176:179], v[118:121]
	v_mfma_f32_16x16x32_bf16 v[114:117], v[168:171], v[176:179], v[114:117]
	v_mfma_f32_16x16x32_bf16 v[102:105], v[160:163], v[184:187], v[102:105]
	v_mfma_f32_16x16x32_bf16 v[98:101], v[168:171], v[184:187], v[98:101]
	v_mfma_f32_16x16x32_bf16 v[86:89], v[160:163], v[192:195], v[86:89]
	v_mfma_f32_16x16x32_bf16 v[82:85], v[168:171], v[192:195], v[82:85]
	v_mfma_f32_16x16x32_bf16 v[70:73], v[160:163], v[200:203], v[70:73]
	v_mfma_f32_16x16x32_bf16 v[66:69], v[168:171], v[200:203], v[66:69]
	v_mfma_f32_16x16x32_bf16 v[118:121], v[164:167], v[180:183], v[118:121]
	v_mfma_f32_16x16x32_bf16 v[114:117], v[172:175], v[180:183], v[114:117]
	v_mfma_f32_16x16x32_bf16 v[102:105], v[164:167], v[188:191], v[102:105]
	v_mfma_f32_16x16x32_bf16 v[98:101], v[172:175], v[188:191], v[98:101]
	v_mfma_f32_16x16x32_bf16 v[86:89], v[164:167], v[196:199], v[86:89]
	v_mfma_f32_16x16x32_bf16 v[82:85], v[172:175], v[196:199], v[82:85]
	v_mfma_f32_16x16x32_bf16 v[70:73], v[164:167], v[204:207], v[70:73]
	v_mfma_f32_16x16x32_bf16 v[66:69], v[172:175], v[204:207], v[66:69]
	s_barrier
	s_setprio 0
	s_add_i32 s10, s15, s7
	s_mov_b32 m0, s10
	ds_read_b128 v[176:179], v147 offset:49152
	ds_read_b128 v[180:183], v147 offset:50176
	ds_read_b128 v[184:187], v147 offset:51200
	ds_read_b128 v[188:191], v147 offset:52224
	ds_read_b128 v[192:195], v147 offset:53248
	ds_read_b128 v[196:199], v147 offset:54272
	ds_read_b128 v[200:203], v147 offset:55296
	ds_read_b128 v[204:207], v147 offset:56320
	global_load_lds_dwordx4 v0, s[98:99]
	s_add_i32 m0, s10, 0x2000
	s_add_i32 s10, s44, s7
	global_load_lds_dwordx4 v134, s[98:99]
	s_mov_b32 m0, s10
	s_nop 0
	global_load_lds_dwordx4 v0, s[100:101]
	s_add_i32 m0, s10, 0x2000
	s_nop 0
	global_load_lds_dwordx4 v134, s[100:101]
	s_mov_b32 m0, s16
	s_nop 0
	global_load_lds_dwordx4 v130, vcc
	s_mov_b32 m0, s17
	s_nop 0
	global_load_lds_dwordx4 v132, vcc
	s_waitcnt vmcnt(8) lgkmcnt(0)
	s_setprio 1
	s_barrier
	v_mfma_f32_16x16x32_bf16 v[62:65], v[140:143], v[176:179], v[62:65]
	v_mfma_f32_16x16x32_bf16 v[58:61], v[152:155], v[176:179], v[58:61]
	v_mfma_f32_16x16x32_bf16 v[46:49], v[140:143], v[184:187], v[46:49]
	v_mfma_f32_16x16x32_bf16 v[42:45], v[152:155], v[184:187], v[42:45]
	v_mfma_f32_16x16x32_bf16 v[30:33], v[140:143], v[192:195], v[30:33]
	v_mfma_f32_16x16x32_bf16 v[26:29], v[152:155], v[192:195], v[26:29]
	v_mfma_f32_16x16x32_bf16 v[14:17], v[140:143], v[200:203], v[14:17]
	v_mfma_f32_16x16x32_bf16 v[10:13], v[152:155], v[200:203], v[10:13]
	v_mfma_f32_16x16x32_bf16 v[62:65], v[148:151], v[180:183], v[62:65]
	v_mfma_f32_16x16x32_bf16 v[58:61], v[156:159], v[180:183], v[58:61]
	v_mfma_f32_16x16x32_bf16 v[46:49], v[148:151], v[188:191], v[46:49]
	v_mfma_f32_16x16x32_bf16 v[42:45], v[156:159], v[188:191], v[42:45]
	v_mfma_f32_16x16x32_bf16 v[30:33], v[148:151], v[196:199], v[30:33]
	v_mfma_f32_16x16x32_bf16 v[26:29], v[156:159], v[196:199], v[26:29]
	v_mfma_f32_16x16x32_bf16 v[14:17], v[148:151], v[204:207], v[14:17]
	v_mfma_f32_16x16x32_bf16 v[10:13], v[156:159], v[204:207], v[10:13]
	v_mfma_f32_16x16x32_bf16 v[54:57], v[160:163], v[176:179], v[54:57]
	v_mfma_f32_16x16x32_bf16 v[50:53], v[168:171], v[176:179], v[50:53]
	v_mfma_f32_16x16x32_bf16 v[38:41], v[160:163], v[184:187], v[38:41]
	v_mfma_f32_16x16x32_bf16 v[34:37], v[168:171], v[184:187], v[34:37]
	v_mfma_f32_16x16x32_bf16 v[22:25], v[160:163], v[192:195], v[22:25]
	v_mfma_f32_16x16x32_bf16 v[18:21], v[168:171], v[192:195], v[18:21]
	v_mfma_f32_16x16x32_bf16 v[6:9], v[160:163], v[200:203], v[6:9]
	v_mfma_f32_16x16x32_bf16 v[2:5], v[168:171], v[200:203], v[2:5]
	v_mfma_f32_16x16x32_bf16 v[54:57], v[164:167], v[180:183], v[54:57]
	v_mfma_f32_16x16x32_bf16 v[50:53], v[172:175], v[180:183], v[50:53]
	v_mfma_f32_16x16x32_bf16 v[38:41], v[164:167], v[188:191], v[38:41]
	v_mfma_f32_16x16x32_bf16 v[34:37], v[172:175], v[188:191], v[34:37]
	v_mfma_f32_16x16x32_bf16 v[22:25], v[164:167], v[196:199], v[22:25]
	v_mfma_f32_16x16x32_bf16 v[18:21], v[172:175], v[196:199], v[18:21]
	v_mfma_f32_16x16x32_bf16 v[6:9], v[164:167], v[204:207], v[6:9]
	v_mfma_f32_16x16x32_bf16 v[2:5], v[172:175], v[204:207], v[2:5]
	s_barrier
	s_setprio 0
	s_add_u32 s8, s8, 0x100
	s_addc_u32 s9, s9, 0
	s_add_u32 s12, s12, 0x100
	s_addc_u32 s13, s13, 0
	s_mov_b32 s10, s14
	.p2align 6

; #define PG8_STAGE(bufoff, gbase, voff) do { _Pragma("unroll") for (int _i = 0; _i < 2; ++_i) \
;         __builtin_amdgcn_global_load_lds((const unsigned*)((const char*)(gbase) + (voff)[_i]), (PG8_LAS unsigned*)(lds + (bufoff) + ldsw + _i * 8192), 16, 0, 0); } while (0)
; #define PG8_LDA(dst, b, h) do { _Pragma("unroll") for (int m = 0; m < 4; ++m) _Pragma("unroll") for (int k = 0; k < 2; ++k) dst[m][k] = *(const PG8_LAS bf16x8*)(lds + PG8_SA(b, h) + aoff + m * 2048 + k * 1024); } while (0)
; #define PG8_LDB(dst, b, h) do { _Pragma("unroll") for (int n = 0; n < 2; ++n) _Pragma("unroll") for (int k = 0; k < 2; ++k) dst[n][k] = *(const PG8_LAS bf16x8*)(lds + PG8_SB(b, h) + boff + n * 2048 + k * 1024); } while (0)
; #define PG8_WAIT_V(n) asm volatile("s_waitcnt vmcnt(" #n ")" ::: "memory")
; #define PG8_WAIT_L(n) asm volatile("s_waitcnt lgkmcnt(" #n ")" ::: "memory")
; #define PG8_BAR __builtin_amdgcn_s_barrier()
; #define PG8_SCHED __builtin_amdgcn_sched_barrier(0)
; template <class Epi, class Sched, bool ALIGN_EPI = false, bool SP2 = false>
; __device__ __forceinline__ void gemm_phase(PG8_LAS unsigned char* lds, const Gemm g, const Sched& S, const Epi& E) {
;     ...
;         const bool has_next = S.next(ui + 1, nxt);
;         const char* nA = has_next ? (const char*)g.A + (size_t)nxt.pm * tstep : cA; const char* nB = has_next ? (const char*)g.Bt + (size_t)nxt.pn * tstep : cB;
;         for (int t = 0; t < nt; t += 2) {
;             const bool last = (t == nt - 2);
;             const char* a1 = cA + (size_t)(t + 1) * kstep;
;             const char* a2 = last ? nA : cA + (size_t)(t + 2) * kstep; const char* b2 = last ? nB : cB + (size_t)(t + 2) * kstep;
;             const char* a3 = a2 + kstep; const char* b3 = b2 + kstep;
;             if (last && has_next) S.a_ready(nxt);
;             if constexpr (SP2) {
;             PG8_LDB(B0, 0, 0); PG8_LDB(B1, 0, 1); PG8_SCHED; PG8_LDA(At, 0, 0); PG8_STAGE(PG8_SA(1, 1), a1 + hstep, voffA);
;             PG8_WAIT_V(8); PG8_WAIT_L(0); PG8_BAR; PG8_MMA(0, 0, At, B0); PG8_MMA(0, 1, At, B1); PG8_BAR; PG8_SCHED;
;             PG8_LDA(At, 0, 1); PG8_STAGE(PG8_SB(0, 0), b2, voffB); PG8_STAGE(PG8_SB(0, 1), b2 + hstep, voffB); PG8_STAGE(PG8_SA(0, 0), a2, voffA);
;             PG8_WAIT_V(8); PG8_WAIT_L(0); PG8_BAR; PG8_MMA(1, 0, At, B0); PG8_MMA(1, 1, At, B1); PG8_BAR; PG8_SCHED;
.Lstg4_done:
	s_ashr_i32 s37, s36, 31
	s_lshl_b64 s[26:27], s[36:37], 20
	s_add_u32 s26, s18, s26
	s_addc_u32 s27, s19, s27
	s_and_b64 s[44:45], s[40:41], exec
	s_cselect_b32 s37, s27, s51
	s_cselect_b32 s43, s26, s50
	s_ashr_i32 s23, s22, 31
	s_lshl_b64 s[44:45], s[22:23], 20
	s_add_u32 s44, s96, s44
	s_addc_u32 s45, s97, s45
	s_and_b64 s[52:53], s[40:41], exec
	s_cselect_b32 s23, s45, s11
	s_cselect_b32 s56, s44, s10
	s_add_u32 s50, s50, 0x80080
	s_addc_u32 s51, s51, 0
	s_add_u32 s57, s10, 0x100
	s_addc_u32 s58, s11, 0
	s_mov_b32 s59, -2
	v_add_u32_e32 v248, 0x10000, v149
	s_add_u32 s10, s50, 0xfff80080
	s_addc_u32 s11, s51, -1
	s_add_i32 s60, 0, 0x10000
	s_cmp_eq_u32 s59, 28
	s_cselect_b32 s53, s37, s11
	s_cselect_b32 s52, s43, s10
	s_cselect_b32 s11, s23, s58
	s_cselect_b32 s10, s56, s57
	s_add_i32 s62, 0, 0x14000
	ds_read_b128 v[140:143], v248
	ds_read_b128 v[152:155], v248 offset:1024
	ds_read_b128 v[156:159], v248 offset:2048
	ds_read_b128 v[160:163], v248 offset:3072
	ds_read_b128 v[164:167], v248 offset:16384
	ds_read_b128 v[168:171], v248 offset:17408
	ds_read_b128 v[172:175], v248 offset:18432
	ds_read_b128 v[176:179], v248 offset:19456
	s_add_i32 m0, s5, 0xc000
	ds_read_b128 v[180:183], v151
	ds_read_b128 v[184:187], v151 offset:1024
	ds_read_b128 v[188:191], v151 offset:2048
	ds_read_b128 v[192:195], v151 offset:3072
	ds_read_b128 v[196:199], v151 offset:4096
	ds_read_b128 v[200:203], v151 offset:5120
	ds_read_b128 v[204:207], v151 offset:6144
	ds_read_b128 v[208:211], v151 offset:7168
	global_load_lds_dwordx4 v136, s[50:51]
	s_add_i32 m0, s5, 0xe000
	s_nop 0
	global_load_lds_dwordx4 v138, s[50:51]
	s_waitcnt vmcnt(8) lgkmcnt(0)
	s_setprio 1
	s_barrier
	v_mfma_f32_16x16x32_bf16 v[126:129], v[140:143], v[180:183], 0
	v_mfma_f32_16x16x32_bf16 v[122:125], v[156:159], v[180:183], 0
	v_mfma_f32_16x16x32_bf16 v[110:113], v[140:143], v[188:191], 0
	v_mfma_f32_16x16x32_bf16 v[106:109], v[156:159], v[188:191], 0
	v_mfma_f32_16x16x32_bf16 v[94:97], v[140:143], v[196:199], 0
	v_mfma_f32_16x16x32_bf16 v[90:93], v[156:159], v[196:199], 0
	v_mfma_f32_16x16x32_bf16 v[78:81], v[140:143], v[204:207], 0
	v_mfma_f32_16x16x32_bf16 v[74:77], v[156:159], v[204:207], 0
	v_mfma_f32_16x16x32_bf16 v[126:129], v[152:155], v[184:187], v[126:129]
	v_mfma_f32_16x16x32_bf16 v[122:125], v[160:163], v[184:187], v[122:125]
	v_mfma_f32_16x16x32_bf16 v[110:113], v[152:155], v[192:195], v[110:113]
	v_mfma_f32_16x16x32_bf16 v[106:109], v[160:163], v[192:195], v[106:109]
	v_mfma_f32_16x16x32_bf16 v[94:97], v[152:155], v[200:203], v[94:97]
	v_mfma_f32_16x16x32_bf16 v[90:93], v[160:163], v[200:203], v[90:93]
	v_mfma_f32_16x16x32_bf16 v[78:81], v[152:155], v[208:211], v[78:81]
	v_mfma_f32_16x16x32_bf16 v[74:77], v[160:163], v[208:211], v[74:77]
	v_mfma_f32_16x16x32_bf16 v[118:121], v[164:167], v[180:183], 0
	v_mfma_f32_16x16x32_bf16 v[114:117], v[172:175], v[180:183], 0
	v_mfma_f32_16x16x32_bf16 v[102:105], v[164:167], v[188:191], 0
	v_mfma_f32_16x16x32_bf16 v[98:101], v[172:175], v[188:191], 0
	v_mfma_f32_16x16x32_bf16 v[86:89], v[164:167], v[196:199], 0
	v_mfma_f32_16x16x32_bf16 v[82:85], v[172:175], v[196:199], 0
	v_mfma_f32_16x16x32_bf16 v[70:73], v[164:167], v[204:207], 0
	v_mfma_f32_16x16x32_bf16 v[66:69], v[172:175], v[204:207], 0
	v_mfma_f32_16x16x32_bf16 v[118:121], v[168:171], v[184:187], v[118:121]
	v_mfma_f32_16x16x32_bf16 v[114:117], v[176:179], v[184:187], v[114:117]
	v_mfma_f32_16x16x32_bf16 v[102:105], v[168:171], v[192:195], v[102:105]
	v_mfma_f32_16x16x32_bf16 v[98:101], v[176:179], v[192:195], v[98:101]
	v_mfma_f32_16x16x32_bf16 v[86:89], v[168:171], v[200:203], v[86:89]
	v_mfma_f32_16x16x32_bf16 v[82:85], v[176:179], v[200:203], v[82:85]
	v_mfma_f32_16x16x32_bf16 v[70:73], v[168:171], v[208:211], v[70:73]
	v_mfma_f32_16x16x32_bf16 v[66:69], v[176:179], v[208:211], v[66:69]
	s_barrier
	s_setprio 0
	s_add_i32 s60, s60, s4
	s_add_u32 s100, s10, 0x80
	s_addc_u32 s101, s11, 0
	s_mov_b32 m0, s60
	ds_read_b128 v[180:183], v151 offset:16384
	ds_read_b128 v[184:187], v151 offset:17408
	ds_read_b128 v[188:191], v151 offset:18432
	ds_read_b128 v[192:195], v151 offset:19456
	ds_read_b128 v[196:199], v151 offset:20480
	ds_read_b128 v[200:203], v151 offset:21504
	ds_read_b128 v[204:207], v151 offset:22528
	ds_read_b128 v[208:211], v151 offset:23552
	global_load_lds_dwordx4 v0, s[10:11]
	s_add_i32 m0, s60, 0x2000
	s_add_u32 s60, s10, 0x80000
	s_addc_u32 s61, s11, 0
	s_add_i32 s62, s62, s4
	global_load_lds_dwordx4 v134, s[10:11]
	s_mov_b32 m0, s62
	s_add_u32 s98, s52, 0x80
	s_addc_u32 s99, s53, 0
	global_load_lds_dwordx4 v0, s[60:61]
	s_add_i32 m0, s62, 0x2000
	s_nop 0
	global_load_lds_dwordx4 v134, s[60:61]
	s_mov_b32 m0, s5
	s_nop 0
	global_load_lds_dwordx4 v130, s[52:53]
	s_mov_b32 m0, s6
	s_nop 0
	global_load_lds_dwordx4 v132, s[52:53]
	s_waitcnt vmcnt(8) lgkmcnt(0)
	s_setprio 1
	s_barrier
; #define PG8_STAGE(bufoff, gbase, voff) do { _Pragma("unroll") for (int _i = 0; _i < 2; ++_i) \
;         __builtin_amdgcn_global_load_lds((const unsigned*)((const char*)(gbase) + (voff)[_i]), (PG8_LAS unsigned*)(lds + (bufoff) + ldsw + _i * 8192), 16, 0, 0); } while (0)
; #define PG8_LDA(dst, b, h) do { _Pragma("unroll") for (int m = 0; m < 4; ++m) _Pragma("unroll") for (int k = 0; k < 2; ++k) dst[m][k] = *(const PG8_LAS bf16x8*)(lds + PG8_SA(b, h) + aoff + m * 2048 + k * 1024); } while (0)
; #define PG8_LDB(dst, b, h) do { _Pragma("unroll") for (int n = 0; n < 2; ++n) _Pragma("unroll") for (int k = 0; k < 2; ++k) dst[n][k] = *(const PG8_LAS bf16x8*)(lds + PG8_SB(b, h) + boff + n * 2048 + k * 1024); } while (0)
; #define PG8_MMA(ai, bj, At, Bt) do { __builtin_amdgcn_s_setprio(1); _Pragma("unroll") for (int m = 0; m < 4; ++m) _Pragma("unroll") for (int n = 0; n < 2; ++n) _Pragma("unroll") for (int k = 0; k < 2; ++k) \
;         acc[ai][bj][m][n] = __builtin_amdgcn_mfma_f32_16x16x32_bf16(Bt[n][k], At[m][k], acc[ai][bj][m][n], 0, 0, 0); __builtin_amdgcn_s_setprio(0); } while (0)
; #define PG8_WAIT_V(n) asm volatile("s_waitcnt vmcnt(" #n ")" ::: "memory")
; #define PG8_WAIT_L(n) asm volatile("s_waitcnt lgkmcnt(" #n ")" ::: "memory")
; #define PG8_BAR __builtin_amdgcn_s_barrier()
; #define PG8_SCHED __builtin_amdgcn_sched_barrier(0)
; template <class Epi, class Sched, bool ALIGN_EPI = false, bool SP2 = false>
; __device__ __forceinline__ void gemm_phase(PG8_LAS unsigned char* lds, const Gemm g, const Sched& S, const Epi& E) {
;     ...
;             PG8_WAIT_V(8); PG8_WAIT_L(0); PG8_BAR; PG8_MMA(0, 0, At, B0); PG8_MMA(0, 1, At, B1); PG8_BAR; PG8_SCHED;
;             PG8_LDA(At, 0, 1); PG8_STAGE(PG8_SB(0, 0), b2, voffB); PG8_STAGE(PG8_SB(0, 1), b2 + hstep, voffB); PG8_STAGE(PG8_SA(0, 0), a2, voffA);
;             PG8_WAIT_V(8); PG8_WAIT_L(0); PG8_BAR; PG8_MMA(1, 0, At, B0); PG8_MMA(1, 1, At, B1); PG8_BAR; PG8_SCHED;
;             PG8_LDB(B0, 1, 0); PG8_LDB(B1, 1, 1); PG8_SCHED; PG8_LDA(At, 1, 0); PG8_STAGE(PG8_SA(0, 1), a2 + hstep, voffA);
;             PG8_WAIT_V(8); PG8_WAIT_L(0); PG8_BAR; PG8_MMA(0, 0, At, B0); PG8_MMA(0, 1, At, B1); PG8_BAR; PG8_SCHED;
	v_mfma_f32_16x16x32_bf16 v[62:65], v[140:143], v[180:183], 0
	v_mfma_f32_16x16x32_bf16 v[58:61], v[156:159], v[180:183], 0
	v_mfma_f32_16x16x32_bf16 v[46:49], v[140:143], v[188:191], 0
	v_mfma_f32_16x16x32_bf16 v[42:45], v[156:159], v[188:191], 0
	v_mfma_f32_16x16x32_bf16 v[30:33], v[140:143], v[196:199], 0
	v_mfma_f32_16x16x32_bf16 v[26:29], v[156:159], v[196:199], 0
	v_mfma_f32_16x16x32_bf16 v[14:17], v[140:143], v[204:207], 0
	v_mfma_f32_16x16x32_bf16 v[10:13], v[156:159], v[204:207], 0
	v_mfma_f32_16x16x32_bf16 v[62:65], v[152:155], v[184:187], v[62:65]
	v_mfma_f32_16x16x32_bf16 v[58:61], v[160:163], v[184:187], v[58:61]
	v_mfma_f32_16x16x32_bf16 v[46:49], v[152:155], v[192:195], v[46:49]
	v_mfma_f32_16x16x32_bf16 v[42:45], v[160:163], v[192:195], v[42:45]
	v_mfma_f32_16x16x32_bf16 v[30:33], v[152:155], v[200:203], v[30:33]
	v_mfma_f32_16x16x32_bf16 v[26:29], v[160:163], v[200:203], v[26:29]
	v_mfma_f32_16x16x32_bf16 v[14:17], v[152:155], v[208:211], v[14:17]
	v_mfma_f32_16x16x32_bf16 v[10:13], v[160:163], v[208:211], v[10:13]
	v_mfma_f32_16x16x32_bf16 v[54:57], v[164:167], v[180:183], 0
	v_mfma_f32_16x16x32_bf16 v[50:53], v[172:175], v[180:183], 0
	v_mfma_f32_16x16x32_bf16 v[38:41], v[164:167], v[188:191], 0
	v_mfma_f32_16x16x32_bf16 v[34:37], v[172:175], v[188:191], 0
	v_mfma_f32_16x16x32_bf16 v[22:25], v[164:167], v[196:199], 0
	v_mfma_f32_16x16x32_bf16 v[18:21], v[172:175], v[196:199], 0
	v_mfma_f32_16x16x32_bf16 v[6:9], v[164:167], v[204:207], 0
	v_mfma_f32_16x16x32_bf16 v[2:5], v[172:175], v[204:207], 0
	v_mfma_f32_16x16x32_bf16 v[54:57], v[168:171], v[184:187], v[54:57]
	v_mfma_f32_16x16x32_bf16 v[50:53], v[176:179], v[184:187], v[50:53]
	v_mfma_f32_16x16x32_bf16 v[38:41], v[168:171], v[192:195], v[38:41]
	v_mfma_f32_16x16x32_bf16 v[34:37], v[176:179], v[192:195], v[34:37]
	v_mfma_f32_16x16x32_bf16 v[22:25], v[168:171], v[200:203], v[22:25]
	v_mfma_f32_16x16x32_bf16 v[18:21], v[176:179], v[200:203], v[18:21]
	v_mfma_f32_16x16x32_bf16 v[6:9], v[168:171], v[208:211], v[6:9]
	v_mfma_f32_16x16x32_bf16 v[2:5], v[176:179], v[208:211], v[2:5]
	s_barrier
	s_setprio 0
	s_add_i32 s60, 0, 0x18000
	s_add_i32 s61, 0, 0x1c000
	ds_read_b128 v[140:143], v248 offset:32768
	ds_read_b128 v[152:155], v248 offset:33792
	ds_read_b128 v[156:159], v248 offset:34816
	ds_read_b128 v[160:163], v248 offset:35840
	ds_read_b128 v[164:167], v248 offset:49152
	ds_read_b128 v[168:171], v248 offset:50176
	ds_read_b128 v[172:175], v248 offset:51200
	ds_read_b128 v[176:179], v248 offset:52224
	s_add_u32 s52, s52, 0x80000
	s_addc_u32 s53, s53, 0
	s_mov_b32 m0, s7
	ds_read_b128 v[180:183], v151 offset:32768
	ds_read_b128 v[184:187], v151 offset:33792
	ds_read_b128 v[188:191], v151 offset:34816
	ds_read_b128 v[192:195], v151 offset:35840
	ds_read_b128 v[196:199], v151 offset:36864
	ds_read_b128 v[200:203], v151 offset:37888
	ds_read_b128 v[204:207], v151 offset:38912
	ds_read_b128 v[208:211], v151 offset:39936
	global_load_lds_dwordx4 v130, s[52:53]
	s_mov_b32 m0, s17
	s_nop 0
	global_load_lds_dwordx4 v132, s[52:53]
	s_waitcnt vmcnt(8) lgkmcnt(0)
	s_setprio 1
	s_barrier
	v_mfma_f32_16x16x32_bf16 v[126:129], v[140:143], v[180:183], v[126:129]
	v_mfma_f32_16x16x32_bf16 v[122:125], v[156:159], v[180:183], v[122:125]
	v_mfma_f32_16x16x32_bf16 v[110:113], v[140:143], v[188:191], v[110:113]
	v_mfma_f32_16x16x32_bf16 v[106:109], v[156:159], v[188:191], v[106:109]
	v_mfma_f32_16x16x32_bf16 v[94:97], v[140:143], v[196:199], v[94:97]
	v_mfma_f32_16x16x32_bf16 v[90:93], v[156:159], v[196:199], v[90:93]
	v_mfma_f32_16x16x32_bf16 v[78:81], v[140:143], v[204:207], v[78:81]
	v_mfma_f32_16x16x32_bf16 v[74:77], v[156:159], v[204:207], v[74:77]
	v_mfma_f32_16x16x32_bf16 v[126:129], v[152:155], v[184:187], v[126:129]
	v_mfma_f32_16x16x32_bf16 v[122:125], v[160:163], v[184:187], v[122:125]
	v_mfma_f32_16x16x32_bf16 v[110:113], v[152:155], v[192:195], v[110:113]
	v_mfma_f32_16x16x32_bf16 v[106:109], v[160:163], v[192:195], v[106:109]
	v_mfma_f32_16x16x32_bf16 v[94:97], v[152:155], v[200:203], v[94:97]
	v_mfma_f32_16x16x32_bf16 v[90:93], v[160:163], v[200:203], v[90:93]
	v_mfma_f32_16x16x32_bf16 v[78:81], v[152:155], v[208:211], v[78:81]
	v_mfma_f32_16x16x32_bf16 v[74:77], v[160:163], v[208:211], v[74:77]
	v_mfma_f32_16x16x32_bf16 v[118:121], v[164:167], v[180:183], v[118:121]
	v_mfma_f32_16x16x32_bf16 v[114:117], v[172:175], v[180:183], v[114:117]
	v_mfma_f32_16x16x32_bf16 v[102:105], v[164:167], v[188:191], v[102:105]
	v_mfma_f32_16x16x32_bf16 v[98:101], v[172:175], v[188:191], v[98:101]
	v_mfma_f32_16x16x32_bf16 v[86:89], v[164:167], v[196:199], v[86:89]
	v_mfma_f32_16x16x32_bf16 v[82:85], v[172:175], v[196:199], v[82:85]
	v_mfma_f32_16x16x32_bf16 v[70:73], v[164:167], v[204:207], v[70:73]
	v_mfma_f32_16x16x32_bf16 v[66:69], v[172:175], v[204:207], v[66:69]
	v_mfma_f32_16x16x32_bf16 v[118:121], v[168:171], v[184:187], v[118:121]
	v_mfma_f32_16x16x32_bf16 v[114:117], v[176:179], v[184:187], v[114:117]
	v_mfma_f32_16x16x32_bf16 v[102:105], v[168:171], v[192:195], v[102:105]
	v_mfma_f32_16x16x32_bf16 v[98:101], v[176:179], v[192:195], v[98:101]
	v_mfma_f32_16x16x32_bf16 v[86:89], v[168:171], v[200:203], v[86:89]
	v_mfma_f32_16x16x32_bf16 v[82:85], v[176:179], v[200:203], v[82:85]
	v_mfma_f32_16x16x32_bf16 v[70:73], v[168:171], v[208:211], v[70:73]
	v_mfma_f32_16x16x32_bf16 v[66:69], v[176:179], v[208:211], v[66:69]
	s_barrier
; #define PG8_STAGE(bufoff, gbase, voff) do { _Pragma("unroll") for (int _i = 0; _i < 2; ++_i) \
;         __builtin_amdgcn_global_load_lds((const unsigned*)((const char*)(gbase) + (voff)[_i]), (PG8_LAS unsigned*)(lds + (bufoff) + ldsw + _i * 8192), 16, 0, 0); } while (0)
; #define PG8_LDA(dst, b, h) do { _Pragma("unroll") for (int m = 0; m < 4; ++m) _Pragma("unroll") for (int k = 0; k < 2; ++k) dst[m][k] = *(const PG8_LAS bf16x8*)(lds + PG8_SA(b, h) + aoff + m * 2048 + k * 1024); } while (0)
; #define PG8_MMA(ai, bj, At, Bt) do { __builtin_amdgcn_s_setprio(1); _Pragma("unroll") for (int m = 0; m < 4; ++m) _Pragma("unroll") for (int n = 0; n < 2; ++n) _Pragma("unroll") for (int k = 0; k < 2; ++k) \
;         acc[ai][bj][m][n] = __builtin_amdgcn_mfma_f32_16x16x32_bf16(Bt[n][k], At[m][k], acc[ai][bj][m][n], 0, 0, 0); __builtin_amdgcn_s_setprio(0); } while (0)
; #define PG8_WAIT_V(n) asm volatile("s_waitcnt vmcnt(" #n ")" ::: "memory")
; #define PG8_WAIT_L(n) asm volatile("s_waitcnt lgkmcnt(" #n ")" ::: "memory")
; #define PG8_BAR __builtin_amdgcn_s_barrier()
; #define PG8_SCHED __builtin_amdgcn_sched_barrier(0)
; template <class Epi, class Sched, bool ALIGN_EPI = false, bool SP2 = false>
; __device__ __forceinline__ void gemm_phase(PG8_LAS unsigned char* lds, const Gemm g, const Sched& S, const Epi& E) {
;     ...
;             PG8_LDA(At, 1, 1); PG8_STAGE(PG8_SB(1, 0), b3, voffB); PG8_STAGE(PG8_SB(1, 1), b3 + hstep, voffB); PG8_STAGE(PG8_SA(1, 0), a3, voffA);
;             PG8_WAIT_V(8); PG8_WAIT_L(0); PG8_BAR; PG8_MMA(1, 0, At, B0); PG8_MMA(1, 1, At, B1); PG8_BAR; PG8_SCHED;
	s_setprio 0
	s_add_i32 s52, s60, s4
	s_mov_b32 m0, s52
	ds_read_b128 v[180:183], v151 offset:49152
	ds_read_b128 v[184:187], v151 offset:50176
	ds_read_b128 v[188:191], v151 offset:51200
	ds_read_b128 v[192:195], v151 offset:52224
	ds_read_b128 v[196:199], v151 offset:53248
	ds_read_b128 v[200:203], v151 offset:54272
	ds_read_b128 v[204:207], v151 offset:55296
	ds_read_b128 v[208:211], v151 offset:56320
	global_load_lds_dwordx4 v0, s[100:101]
	s_add_i32 m0, s52, 0x2000
	s_add_i32 s52, s61, s4
	global_load_lds_dwordx4 v134, s[100:101]
	s_add_u32 s10, s10, 0x80080
	s_addc_u32 s11, s11, 0
	s_mov_b32 m0, s52
	s_nop 0
	global_load_lds_dwordx4 v0, s[10:11]
	s_add_i32 m0, s52, 0x2000
	s_nop 0
	global_load_lds_dwordx4 v134, s[10:11]
	s_mov_b32 m0, s30
	s_nop 0
	global_load_lds_dwordx4 v130, s[98:99]
	s_mov_b32 m0, s47
	s_nop 0
	global_load_lds_dwordx4 v132, s[98:99]
	s_waitcnt vmcnt(8) lgkmcnt(0)
	s_setprio 1
	s_barrier
	v_mfma_f32_16x16x32_bf16 v[62:65], v[140:143], v[180:183], v[62:65]
	v_mfma_f32_16x16x32_bf16 v[58:61], v[156:159], v[180:183], v[58:61]
	v_mfma_f32_16x16x32_bf16 v[46:49], v[140:143], v[188:191], v[46:49]
	v_mfma_f32_16x16x32_bf16 v[42:45], v[156:159], v[188:191], v[42:45]
	v_mfma_f32_16x16x32_bf16 v[30:33], v[140:143], v[196:199], v[30:33]
	v_mfma_f32_16x16x32_bf16 v[26:29], v[156:159], v[196:199], v[26:29]
	v_mfma_f32_16x16x32_bf16 v[14:17], v[140:143], v[204:207], v[14:17]
	v_mfma_f32_16x16x32_bf16 v[10:13], v[156:159], v[204:207], v[10:13]
	v_mfma_f32_16x16x32_bf16 v[62:65], v[152:155], v[184:187], v[62:65]
	v_mfma_f32_16x16x32_bf16 v[58:61], v[160:163], v[184:187], v[58:61]
	v_mfma_f32_16x16x32_bf16 v[46:49], v[152:155], v[192:195], v[46:49]
	v_mfma_f32_16x16x32_bf16 v[42:45], v[160:163], v[192:195], v[42:45]
	v_mfma_f32_16x16x32_bf16 v[30:33], v[152:155], v[200:203], v[30:33]
	v_mfma_f32_16x16x32_bf16 v[26:29], v[160:163], v[200:203], v[26:29]
	v_mfma_f32_16x16x32_bf16 v[14:17], v[152:155], v[208:211], v[14:17]
	v_mfma_f32_16x16x32_bf16 v[10:13], v[160:163], v[208:211], v[10:13]
	v_mfma_f32_16x16x32_bf16 v[54:57], v[164:167], v[180:183], v[54:57]
	v_mfma_f32_16x16x32_bf16 v[50:53], v[172:175], v[180:183], v[50:53]
	v_mfma_f32_16x16x32_bf16 v[38:41], v[164:167], v[188:191], v[38:41]
	v_mfma_f32_16x16x32_bf16 v[34:37], v[172:175], v[188:191], v[34:37]
	v_mfma_f32_16x16x32_bf16 v[22:25], v[164:167], v[196:199], v[22:25]
	v_mfma_f32_16x16x32_bf16 v[18:21], v[172:175], v[196:199], v[18:21]
	v_mfma_f32_16x16x32_bf16 v[6:9], v[164:167], v[204:207], v[6:9]
	v_mfma_f32_16x16x32_bf16 v[2:5], v[172:175], v[204:207], v[2:5]
	v_mfma_f32_16x16x32_bf16 v[54:57], v[168:171], v[184:187], v[54:57]
	v_mfma_f32_16x16x32_bf16 v[50:53], v[176:179], v[184:187], v[50:53]
	v_mfma_f32_16x16x32_bf16 v[38:41], v[168:171], v[192:195], v[38:41]
	v_mfma_f32_16x16x32_bf16 v[34:37], v[176:179], v[192:195], v[34:37]
	v_mfma_f32_16x16x32_bf16 v[22:25], v[168:171], v[200:203], v[22:25]
	v_mfma_f32_16x16x32_bf16 v[18:21], v[176:179], v[200:203], v[18:21]
	v_mfma_f32_16x16x32_bf16 v[6:9], v[168:171], v[208:211], v[6:9]
	v_mfma_f32_16x16x32_bf16 v[2:5], v[176:179], v[208:211], v[2:5]
	s_barrier
	s_setprio 0
	s_add_i32 s59, s59, 2
	s_add_u32 s50, s50, 0x100
	s_addc_u32 s51, s51, 0
	s_add_u32 s57, s57, 0x100
	s_addc_u32 s58, s58, 0
	.p2align 6
